# P0: the seven weight-conversion calls are active on rotated workgroup ranges so they run concurrently across the chip (max 4 active calls per workgroup instead of 8)
# speedup vs baseline: 1.0087x; 1.0085x over previous
.LBB0_104:
	s_or_b64 exec, exec, s[4:5]
	s_mov_b32 s97, s30
	v_readlane_b32 s0, v246, 1
	s_lshl_b32 s16, s0, 9
	v_lshl_add_u32 v36, s30, 9, v202
	s_mov_b32 s0, 0x16000
	v_cmp_gt_i32_e64 s[4:5], s0, v36
	v_readlane_b32 s1, v246, 2
	s_and_saveexec_b64 s[6:7], s[4:5]
	s_cbranch_execz .LBB0_123
	v_readlane_b32 s36, v246, 22
	v_readlane_b32 s37, v246, 23
	s_cmp_lg_u64 s[36:37], 0
	s_cselect_b64 s[0:1], -1, 0
	v_lshlrev_b32_e32 v0, 3, v202
	v_readlane_b32 s10, v246, 1
	v_lshl_add_u32 v37, s30, 12, v0
	v_readlane_b32 s11, v246, 2
	v_cndmask_b32_e64 v0, 0, 1, s[0:1]
	s_mov_b64 s[8:9], 0
	s_lshl_b32 s10, s10, 12
	s_mov_b32 s11, 0x2e8ba2e9
	s_movk_i32 s12, 0x58
	s_movk_i32 s13, 0x2c00
	v_cmp_ne_u32_e64 s[0:1], 1, v0
	s_mov_b32 s14, 0x15fff
	v_mov_b32_e32 v38, v36
	v_readlane_b32 s38, v246, 24
	v_readlane_b32 s39, v246, 25
	v_readlane_b32 s40, v246, 26
	v_readlane_b32 s41, v246, 27
	v_readlane_b32 s42, v246, 28
	v_readlane_b32 s43, v246, 29
	v_readlane_b32 s44, v246, 30
	v_readlane_b32 s45, v246, 31
	v_readlane_b32 s46, v246, 32
	v_readlane_b32 s47, v246, 33
	v_readlane_b32 s48, v246, 34
	v_readlane_b32 s49, v246, 35
	v_readlane_b32 s50, v246, 36
	v_readlane_b32 s51, v246, 37
	s_branch .LBB0_107

.LBB0_126:
	s_or_b64 exec, exec, s[0:1]
	s_add_i32 s30, s97, 192
	s_and_b32 s30, s30, 0xff
	v_lshl_add_u32 v36, s30, 9, v202
	s_movk_i32 s0, 0x4000
	v_cmp_gt_i32_e64 s[0:1], s0, v36
	s_and_saveexec_b64 s[10:11], s[0:1]
	s_cbranch_execz .LBB0_145
	s_add_u32 s12, s22, 0x780000
	v_readlane_b32 s36, v246, 22
	s_addc_u32 s13, s23, 0
	v_readlane_b32 s48, v246, 34
	v_readlane_b32 s49, v246, 35
	s_cmp_lg_u64 s[48:49], 0
	s_cselect_b64 s[8:9], -1, 0
	v_lshlrev_b32_e32 v0, 3, v202
	v_readlane_b32 s18, v246, 1
	v_lshl_add_u32 v37, s30, 12, v0
	v_readlane_b32 s19, v246, 2
	v_cndmask_b32_e64 v0, 0, 1, s[8:9]
	s_mov_b64 s[14:15], 0
	s_lshl_b32 s17, s18, 12
	s_movk_i32 s18, 0xffc0
	v_cmp_ne_u32_e64 s[8:9], 1, v0
	s_movk_i32 s19, 0x3fff
	v_mov_b32_e32 v38, v36
	v_readlane_b32 s37, v246, 23
	v_readlane_b32 s38, v246, 24
	v_readlane_b32 s39, v246, 25
	v_readlane_b32 s40, v246, 26
	v_readlane_b32 s41, v246, 27
	v_readlane_b32 s42, v246, 28
	v_readlane_b32 s43, v246, 29
	v_readlane_b32 s44, v246, 30
	v_readlane_b32 s45, v246, 31
	v_readlane_b32 s46, v246, 32
	v_readlane_b32 s47, v246, 33
	v_readlane_b32 s50, v246, 36
	v_readlane_b32 s51, v246, 37
	s_branch .LBB0_129

.LBB0_145:
	s_or_b64 exec, exec, s[10:11]
	s_add_i32 s30, s97, 0
	s_and_b32 s30, s30, 0xff
	v_lshl_add_u32 v36, s30, 9, v202
	s_mov_b32 s96, 0x8000
	v_cmp_gt_i32_e64 s[6:7], s96, v36
	s_and_saveexec_b64 s[8:9], s[6:7]
	s_cbranch_execz .LBB0_164
	s_add_u32 s10, s22, 0x880000
	v_readlane_b32 s36, v246, 22
	s_addc_u32 s11, s23, 0
	v_readlane_b32 s50, v246, 36
	v_readlane_b32 s51, v246, 37
	s_cmp_lg_u64 s[50:51], 0
	s_cselect_b64 s[6:7], -1, 0
	v_lshlrev_b32_e32 v0, 3, v202
	v_readlane_b32 s14, v246, 1
	v_lshl_add_u32 v37, s30, 12, v0
	v_readlane_b32 s15, v246, 2
	v_cndmask_b32_e64 v0, 0, 1, s[6:7]
	s_mov_b64 s[12:13], 0
	s_lshl_b32 s14, s14, 12
	s_movk_i32 s15, 0xffc0
	v_cmp_ne_u32_e64 s[6:7], 1, v0
	s_movk_i32 s17, 0x7fff
	v_mov_b32_e32 v38, v36
	v_readlane_b32 s37, v246, 23
	v_readlane_b32 s38, v246, 24
	v_readlane_b32 s39, v246, 25
	v_readlane_b32 s40, v246, 26
	v_readlane_b32 s41, v246, 27
	v_readlane_b32 s42, v246, 28
	v_readlane_b32 s43, v246, 29
	v_readlane_b32 s44, v246, 30
	v_readlane_b32 s45, v246, 31
	v_readlane_b32 s46, v246, 32
	v_readlane_b32 s47, v246, 33
	v_readlane_b32 s48, v246, 34
	v_readlane_b32 s49, v246, 35
	s_branch .LBB0_148

.LBB0_164:
	s_or_b64 exec, exec, s[8:9]
	s_add_i32 s30, s97, 80
	s_and_b32 s30, s30, 0xff
	v_lshl_add_u32 v36, s30, 9, v202
	s_movk_i32 s96, 0x4000
	v_cmp_gt_i32_e64 s[0:1], s96, v36
	s_and_saveexec_b64 s[6:7], s[0:1]
	v_readlane_b32 s36, v246, 38
	v_readlane_b32 s44, v246, 46
	v_readlane_b32 s45, v246, 47
	v_readlane_b32 s37, v246, 39
	v_readlane_b32 s38, v246, 40
	v_readlane_b32 s39, v246, 41
	v_readlane_b32 s40, v246, 42
	v_readlane_b32 s41, v246, 43
	v_readlane_b32 s42, v246, 44
	v_readlane_b32 s43, v246, 45
	v_readlane_b32 s46, v246, 48
	v_readlane_b32 s47, v246, 49
	v_readlane_b32 s48, v246, 50
	v_readlane_b32 s49, v246, 51
	v_readlane_b32 s50, v246, 52
	v_readlane_b32 s51, v246, 53
	s_cbranch_execz .LBB0_167
	v_readlane_b32 s8, v246, 1
	s_add_u32 s0, s22, 0xa80000
	v_lshlrev_b32_e32 v0, 3, v202
	v_readlane_b32 s9, v246, 2
	s_addc_u32 s1, s23, 0
	v_lshl_add_u32 v0, s30, 12, v0
	s_lshl_b32 s10, s8, 12
	s_mov_b64 s[8:9], 0
	s_movk_i32 s11, 0xffc0
	s_movk_i32 s12, 0x3fff
	v_mov_b32_e32 v1, v36

.LBB0_167:
	s_or_b64 exec, exec, s[6:7]
	s_add_i32 s30, s97, 96
	s_and_b32 s30, s30, 0xff
	v_lshl_add_u32 v36, s30, 9, v202
	s_mov_b32 s0, 0x2c000
	v_cmp_gt_i32_e32 vcc, s0, v36
	s_and_saveexec_b64 s[6:7], vcc
	s_cbranch_execz .LBB0_186
	s_add_u32 s8, s22, 0xb80000
	v_readlane_b32 s36, v246, 38
	s_addc_u32 s9, s23, 0
	v_readlane_b32 s46, v246, 48
	v_readlane_b32 s47, v246, 49
	s_cmp_lg_u64 s[46:47], 0
	s_cselect_b64 s[0:1], -1, 0
	v_lshlrev_b32_e32 v0, 3, v202
	v_readlane_b32 s12, v246, 1
	v_lshl_add_u32 v37, s30, 12, v0
	v_readlane_b32 s13, v246, 2
	v_cndmask_b32_e64 v0, 0, 1, s[0:1]
	s_mov_b64 s[10:11], 0
	s_lshl_b32 s12, s12, 12
	s_mov_b32 s13, 0x2e8ba2e9
	s_movk_i32 s14, 0xb0
	s_movk_i32 s15, 0x60
	s_movk_i32 s17, 0x5800
	v_cmp_ne_u32_e64 s[0:1], 1, v0
	s_mov_b32 s18, 0x2bfff
	v_mov_b32_e32 v38, v36
	v_readlane_b32 s37, v246, 39
	v_readlane_b32 s38, v246, 40
	v_readlane_b32 s39, v246, 41
	v_readlane_b32 s40, v246, 42
	v_readlane_b32 s41, v246, 43
	v_readlane_b32 s42, v246, 44
	v_readlane_b32 s43, v246, 45
	v_readlane_b32 s44, v246, 46
	v_readlane_b32 s45, v246, 47
	v_readlane_b32 s48, v246, 50
	v_readlane_b32 s49, v246, 51
	v_readlane_b32 s50, v246, 52
	v_readlane_b32 s51, v246, 53
	s_branch .LBB0_170

.LBB0_186:
	s_or_b64 exec, exec, s[6:7]
	s_add_i32 s30, s97, 176
	s_and_b32 s30, s30, 0xff
	v_lshl_add_u32 v36, s30, 9, v202
	s_mov_b32 s96, 0x16000
	v_cmp_gt_i32_e64 s[4:5], s96, v36
	s_and_saveexec_b64 s[0:1], s[4:5]
	v_readlane_b32 s36, v246, 38
	v_readlane_b32 s50, v246, 52
	v_readlane_b32 s51, v246, 53
	v_readlane_b32 s37, v246, 39
	v_readlane_b32 s38, v246, 40
	v_readlane_b32 s39, v246, 41
	v_readlane_b32 s40, v246, 42
	v_readlane_b32 s41, v246, 43
	v_readlane_b32 s42, v246, 44
	v_readlane_b32 s43, v246, 45
	v_readlane_b32 s44, v246, 46
	v_readlane_b32 s45, v246, 47
	v_readlane_b32 s46, v246, 48
	v_readlane_b32 s47, v246, 49
	v_readlane_b32 s48, v246, 50
	v_readlane_b32 s49, v246, 51
	s_cbranch_execz .LBB0_189
	v_readlane_b32 s6, v246, 1
	s_add_u32 s4, s22, 0x1680000
	v_lshlrev_b32_e32 v0, 3, v202
	v_readlane_b32 s7, v246, 2
	s_mov_b64 s[18:19], s[50:51]
	s_addc_u32 s5, s23, 0
	v_lshl_add_u32 v0, s30, 12, v0
	s_lshl_b32 s8, s6, 12
	s_mov_b64 s[6:7], 0
	s_movk_i32 s9, 0xffc0
	s_movk_i32 s10, 0xb00
	s_movk_i32 s11, 0x1000
	s_movk_i32 s12, 0x2000
	s_mov_b32 s13, 0x15fff

.LBB0_189:
	s_or_b64 exec, exec, s[0:1]
	s_mov_b32 s30, s97
